# P1 epilogue stores also default-cached instead of nt (on top of default-cached final output stores)
# speedup vs baseline: 1.0065x; 1.0020x over previous
.LBB0_263:
	s_cmp_gt_u32 s6, 7
	v_ashrrev_i32_e32 v163, 31, v162
	s_cselect_b64 s[8:9], -1, 0
	v_lshlrev_b64 v[166:167], 8, v[162:163]
	s_waitcnt vmcnt(0)
	v_pk_mul_f32 v[138:139], v[122:123], v[134:135]
	v_pk_mul_f32 v[136:137], v[120:121], v[132:133]
	v_pk_mul_f32 v[142:143], v[126:127], v[134:135]
	v_pk_mul_f32 v[140:141], v[124:125], v[132:133]
	v_cndmask_b32_e64 v164, 0, 1, s[4:5]
	v_or_b32_e32 v166, v166, v150
	v_pk_fma_f32 v[136:137], v[124:125], v[128:129], v[136:137] neg_lo:[0,0,1] neg_hi:[0,0,1]
	v_pk_fma_f32 v[138:139], v[126:127], v[130:131], v[138:139] neg_lo:[0,0,1] neg_hi:[0,0,1]
	v_pk_fma_f32 v[140:141], v[120:121], v[128:129], v[140:141]
	v_pk_fma_f32 v[142:143], v[122:123], v[130:131], v[142:143]
	s_mov_b64 s[6:7], -1
	s_and_b64 vcc, exec, s[8:9]
	v_cmp_ne_u32_e64 s[4:5], 1, v164
	s_cbranch_vccz .LBB0_267
	v_cvt_pk_bf16_f32 v164, v136, v137
	v_cvt_pk_bf16_f32 v165, v138, v139
	v_lshl_add_u64 v[168:169], v[166:167], 1, s[22:23]
	global_store_dwordx2 v[168:169], v[164:165], off
	v_cvt_pk_bf16_f32 v164, v140, v141
	v_cvt_pk_bf16_f32 v165, v142, v143
	s_and_b64 vcc, exec, s[4:5]
	global_store_dwordx2 v[168:169], v[164:165], off offset:64
	s_cbranch_vccnz .LBB0_266
	v_lshl_add_u64 v[164:165], v[166:167], 2, s[56:57]
	global_store_dwordx4 v[164:165], v[136:139], off
	global_store_dwordx4 v[164:165], v[140:143], off offset:128

.LBB0_269:
	v_pk_mul_f32 v[136:137], v[114:115], v[134:135]
	v_pk_mul_f32 v[140:141], v[112:113], v[132:133]
	v_pk_mul_f32 v[132:133], v[116:117], v[132:133]
	v_pk_fma_f32 v[138:139], v[118:119], v[130:131], v[136:137] neg_lo:[0,0,1] neg_hi:[0,0,1]
	v_pk_fma_f32 v[136:137], v[116:117], v[128:129], v[140:141] neg_lo:[0,0,1] neg_hi:[0,0,1]
	v_pk_mul_f32 v[134:135], v[118:119], v[134:135]
	v_pk_fma_f32 v[128:129], v[112:113], v[128:129], v[132:133]
	v_cndmask_b32_e64 v132, 0, 1, s[8:9]
	v_pk_fma_f32 v[130:131], v[114:115], v[130:131], v[134:135]
	v_cmp_ne_u32_e64 s[6:7], 1, v132
	s_andn2_b64 vcc, exec, s[8:9]
	s_mov_b64 s[8:9], -1
	s_cbranch_vccnz .LBB0_275
	v_or_b32_e32 v166, 0x80, v166
	v_cvt_pk_bf16_f32 v132, v136, v137
	v_cvt_pk_bf16_f32 v133, v138, v139
	v_lshl_add_u64 v[134:135], v[166:167], 1, s[22:23]
	global_store_dwordx2 v[134:135], v[132:133], off
	v_cvt_pk_bf16_f32 v132, v128, v129
	v_cvt_pk_bf16_f32 v133, v130, v131
	s_and_b64 vcc, exec, s[4:5]
	global_store_dwordx2 v[134:135], v[132:133], off offset:64
	s_cbranch_vccnz .LBB0_272
	v_lshl_add_u64 v[132:133], v[166:167], 2, s[56:57]
	global_store_dwordx4 v[132:133], v[136:139], off
	global_store_dwordx4 v[132:133], v[128:131], off offset:128

.LBB0_278:
	v_or_b32_e32 v168, 16, v162
	v_ashrrev_i32_e32 v169, 31, v168
	v_lshlrev_b64 v[166:167], 8, v[168:169]
	s_waitcnt vmcnt(0)
	v_pk_mul_f32 v[138:139], v[106:107], v[134:135]
	v_pk_mul_f32 v[136:137], v[104:105], v[132:133]
	v_pk_mul_f32 v[142:143], v[110:111], v[134:135]
	v_pk_mul_f32 v[140:141], v[108:109], v[132:133]
	v_or_b32_e32 v166, v166, v150
	v_pk_fma_f32 v[136:137], v[108:109], v[128:129], v[136:137] neg_lo:[0,0,1] neg_hi:[0,0,1]
	v_pk_fma_f32 v[138:139], v[110:111], v[130:131], v[138:139] neg_lo:[0,0,1] neg_hi:[0,0,1]
	v_pk_fma_f32 v[140:141], v[104:105], v[128:129], v[140:141]
	v_pk_fma_f32 v[142:143], v[106:107], v[130:131], v[142:143]
	s_and_b64 vcc, exec, s[6:7]
	s_mov_b64 s[26:27], -1
	s_cbranch_vccnz .LBB0_282
	v_cvt_pk_bf16_f32 v176, v136, v137
	v_cvt_pk_bf16_f32 v177, v138, v139
	v_lshl_add_u64 v[178:179], v[166:167], 1, s[22:23]
	global_store_dwordx2 v[178:179], v[176:177], off
	v_cvt_pk_bf16_f32 v176, v140, v141
	v_cvt_pk_bf16_f32 v177, v142, v143
	s_and_b64 vcc, exec, s[4:5]
	global_store_dwordx2 v[178:179], v[176:177], off offset:64
	s_cbranch_vccnz .LBB0_281
	v_lshl_add_u64 v[176:177], v[166:167], 2, s[56:57]
	global_store_dwordx4 v[176:177], v[136:139], off
	global_store_dwordx4 v[176:177], v[140:143], off offset:128

.LBB0_284:
	v_pk_mul_f32 v[136:137], v[98:99], v[134:135]
	v_pk_mul_f32 v[140:141], v[96:97], v[132:133]
	v_pk_mul_f32 v[134:135], v[102:103], v[134:135]
	v_pk_mul_f32 v[132:133], v[100:101], v[132:133]
	v_pk_fma_f32 v[138:139], v[102:103], v[130:131], v[136:137] neg_lo:[0,0,1] neg_hi:[0,0,1]
	v_pk_fma_f32 v[136:137], v[100:101], v[128:129], v[140:141] neg_lo:[0,0,1] neg_hi:[0,0,1]
	v_pk_fma_f32 v[130:131], v[98:99], v[130:131], v[134:135]
	v_pk_fma_f32 v[128:129], v[96:97], v[128:129], v[132:133]
	s_and_b64 vcc, exec, s[6:7]
	s_mov_b64 s[26:27], -1
	s_cbranch_vccnz .LBB0_290
	v_or_b32_e32 v166, 0x80, v166
	v_cvt_pk_bf16_f32 v132, v136, v137
	v_cvt_pk_bf16_f32 v133, v138, v139
	v_lshl_add_u64 v[134:135], v[166:167], 1, s[22:23]
	global_store_dwordx2 v[134:135], v[132:133], off
	v_cvt_pk_bf16_f32 v132, v128, v129
	v_cvt_pk_bf16_f32 v133, v130, v131
	s_and_b64 vcc, exec, s[4:5]
	global_store_dwordx2 v[134:135], v[132:133], off offset:64
	s_cbranch_vccnz .LBB0_287
	v_lshl_add_u64 v[132:133], v[166:167], 2, s[56:57]
	global_store_dwordx4 v[132:133], v[136:139], off
	global_store_dwordx4 v[132:133], v[128:131], off offset:128

.LBB0_293:
	v_or_b32_e32 v168, 32, v162
	v_ashrrev_i32_e32 v169, 31, v168
	v_lshlrev_b64 v[166:167], 8, v[168:169]
	s_waitcnt vmcnt(0)
	v_pk_mul_f32 v[138:139], v[90:91], v[134:135]
	v_pk_mul_f32 v[136:137], v[88:89], v[132:133]
	v_pk_mul_f32 v[142:143], v[94:95], v[134:135]
	v_pk_mul_f32 v[140:141], v[92:93], v[132:133]
	v_or_b32_e32 v166, v166, v150
	v_pk_fma_f32 v[136:137], v[92:93], v[128:129], v[136:137] neg_lo:[0,0,1] neg_hi:[0,0,1]
	v_pk_fma_f32 v[138:139], v[94:95], v[130:131], v[138:139] neg_lo:[0,0,1] neg_hi:[0,0,1]
	v_pk_fma_f32 v[140:141], v[88:89], v[128:129], v[140:141]
	v_pk_fma_f32 v[142:143], v[90:91], v[130:131], v[142:143]
	s_and_b64 vcc, exec, s[6:7]
	s_mov_b64 s[26:27], -1
	s_cbranch_vccnz .LBB0_297
	v_cvt_pk_bf16_f32 v176, v136, v137
	v_cvt_pk_bf16_f32 v177, v138, v139
	v_lshl_add_u64 v[178:179], v[166:167], 1, s[22:23]
	global_store_dwordx2 v[178:179], v[176:177], off
	v_cvt_pk_bf16_f32 v176, v140, v141
	v_cvt_pk_bf16_f32 v177, v142, v143
	s_and_b64 vcc, exec, s[4:5]
	global_store_dwordx2 v[178:179], v[176:177], off offset:64
	s_cbranch_vccnz .LBB0_296
	v_lshl_add_u64 v[176:177], v[166:167], 2, s[56:57]
	global_store_dwordx4 v[176:177], v[136:139], off
	global_store_dwordx4 v[176:177], v[140:143], off offset:128

.LBB0_299:
	v_pk_mul_f32 v[136:137], v[82:83], v[134:135]
	v_pk_mul_f32 v[140:141], v[80:81], v[132:133]
	v_pk_mul_f32 v[134:135], v[86:87], v[134:135]
	v_pk_mul_f32 v[132:133], v[84:85], v[132:133]
	v_pk_fma_f32 v[138:139], v[86:87], v[130:131], v[136:137] neg_lo:[0,0,1] neg_hi:[0,0,1]
	v_pk_fma_f32 v[136:137], v[84:85], v[128:129], v[140:141] neg_lo:[0,0,1] neg_hi:[0,0,1]
	v_pk_fma_f32 v[130:131], v[82:83], v[130:131], v[134:135]
	v_pk_fma_f32 v[128:129], v[80:81], v[128:129], v[132:133]
	s_and_b64 vcc, exec, s[6:7]
	s_mov_b64 s[26:27], -1
	s_cbranch_vccnz .LBB0_305
	v_or_b32_e32 v166, 0x80, v166
	v_cvt_pk_bf16_f32 v132, v136, v137
	v_cvt_pk_bf16_f32 v133, v138, v139
	v_lshl_add_u64 v[134:135], v[166:167], 1, s[22:23]
	global_store_dwordx2 v[134:135], v[132:133], off
	v_cvt_pk_bf16_f32 v132, v128, v129
	v_cvt_pk_bf16_f32 v133, v130, v131
	s_and_b64 vcc, exec, s[4:5]
	global_store_dwordx2 v[134:135], v[132:133], off offset:64
	s_cbranch_vccnz .LBB0_302
	v_lshl_add_u64 v[132:133], v[166:167], 2, s[56:57]
	global_store_dwordx4 v[132:133], v[136:139], off
	global_store_dwordx4 v[132:133], v[128:131], off offset:128

.LBB0_308:
	v_or_b32_e32 v168, 48, v162
	v_ashrrev_i32_e32 v169, 31, v168
	v_lshlrev_b64 v[166:167], 8, v[168:169]
	s_waitcnt vmcnt(0)
	v_pk_mul_f32 v[138:139], v[74:75], v[134:135]
	v_pk_mul_f32 v[136:137], v[72:73], v[132:133]
	v_pk_mul_f32 v[142:143], v[78:79], v[134:135]
	v_pk_mul_f32 v[140:141], v[76:77], v[132:133]
	v_or_b32_e32 v166, v166, v150
	v_pk_fma_f32 v[136:137], v[76:77], v[128:129], v[136:137] neg_lo:[0,0,1] neg_hi:[0,0,1]
	v_pk_fma_f32 v[138:139], v[78:79], v[130:131], v[138:139] neg_lo:[0,0,1] neg_hi:[0,0,1]
	v_pk_fma_f32 v[140:141], v[72:73], v[128:129], v[140:141]
	v_pk_fma_f32 v[142:143], v[74:75], v[130:131], v[142:143]
	s_and_b64 vcc, exec, s[6:7]
	s_mov_b64 s[26:27], -1
	s_cbranch_vccnz .LBB0_312
	v_cvt_pk_bf16_f32 v176, v136, v137
	v_cvt_pk_bf16_f32 v177, v138, v139
	v_lshl_add_u64 v[178:179], v[166:167], 1, s[22:23]
	global_store_dwordx2 v[178:179], v[176:177], off
	v_cvt_pk_bf16_f32 v176, v140, v141
	v_cvt_pk_bf16_f32 v177, v142, v143
	s_and_b64 vcc, exec, s[4:5]
	global_store_dwordx2 v[178:179], v[176:177], off offset:64
	s_cbranch_vccnz .LBB0_311
	v_lshl_add_u64 v[176:177], v[166:167], 2, s[56:57]
	global_store_dwordx4 v[176:177], v[136:139], off
	global_store_dwordx4 v[176:177], v[140:143], off offset:128

.LBB0_314:
	v_pk_mul_f32 v[136:137], v[66:67], v[134:135]
	v_pk_mul_f32 v[140:141], v[64:65], v[132:133]
	v_pk_mul_f32 v[134:135], v[70:71], v[134:135]
	v_pk_mul_f32 v[132:133], v[68:69], v[132:133]
	v_pk_fma_f32 v[138:139], v[70:71], v[130:131], v[136:137] neg_lo:[0,0,1] neg_hi:[0,0,1]
	v_pk_fma_f32 v[136:137], v[68:69], v[128:129], v[140:141] neg_lo:[0,0,1] neg_hi:[0,0,1]
	v_pk_fma_f32 v[130:131], v[66:67], v[130:131], v[134:135]
	v_pk_fma_f32 v[128:129], v[64:65], v[128:129], v[132:133]
	s_and_b64 vcc, exec, s[6:7]
	s_mov_b64 s[26:27], -1
	s_cbranch_vccnz .LBB0_320
	v_or_b32_e32 v166, 0x80, v166
	v_cvt_pk_bf16_f32 v132, v136, v137
	v_cvt_pk_bf16_f32 v133, v138, v139
	v_lshl_add_u64 v[134:135], v[166:167], 1, s[22:23]
	global_store_dwordx2 v[134:135], v[132:133], off
	v_cvt_pk_bf16_f32 v132, v128, v129
	v_cvt_pk_bf16_f32 v133, v130, v131
	s_and_b64 vcc, exec, s[4:5]
	global_store_dwordx2 v[134:135], v[132:133], off offset:64
	s_cbranch_vccnz .LBB0_317
	v_lshl_add_u64 v[132:133], v[166:167], 2, s[56:57]
	global_store_dwordx4 v[132:133], v[136:139], off
	global_store_dwordx4 v[132:133], v[128:131], off offset:128

.LBB0_323:
	v_ashrrev_i32_e32 v169, 31, v168
	v_lshlrev_b64 v[166:167], 8, v[168:169]
	s_waitcnt vmcnt(0)
	v_pk_mul_f32 v[138:139], v[58:59], v[134:135]
	v_pk_mul_f32 v[136:137], v[56:57], v[132:133]
	v_pk_mul_f32 v[142:143], v[62:63], v[134:135]
	v_pk_mul_f32 v[140:141], v[60:61], v[132:133]
	v_or_b32_e32 v166, v166, v150
	v_pk_fma_f32 v[136:137], v[60:61], v[128:129], v[136:137] neg_lo:[0,0,1] neg_hi:[0,0,1]
	v_pk_fma_f32 v[138:139], v[62:63], v[130:131], v[138:139] neg_lo:[0,0,1] neg_hi:[0,0,1]
	v_pk_fma_f32 v[140:141], v[56:57], v[128:129], v[140:141]
	v_pk_fma_f32 v[142:143], v[58:59], v[130:131], v[142:143]
	s_and_b64 vcc, exec, s[6:7]
	s_mov_b64 s[26:27], -1
	s_cbranch_vccnz .LBB0_327
	v_cvt_pk_bf16_f32 v176, v136, v137
	v_cvt_pk_bf16_f32 v177, v138, v139
	v_lshl_add_u64 v[178:179], v[166:167], 1, s[22:23]
	global_store_dwordx2 v[178:179], v[176:177], off
	v_cvt_pk_bf16_f32 v176, v140, v141
	v_cvt_pk_bf16_f32 v177, v142, v143
	s_and_b64 vcc, exec, s[4:5]
	global_store_dwordx2 v[178:179], v[176:177], off offset:64
	s_cbranch_vccnz .LBB0_326
	v_lshl_add_u64 v[176:177], v[166:167], 2, s[56:57]
	global_store_dwordx4 v[176:177], v[136:139], off
	global_store_dwordx4 v[176:177], v[140:143], off offset:128

.LBB0_329:
	v_pk_mul_f32 v[136:137], v[50:51], v[134:135]
	v_pk_mul_f32 v[140:141], v[48:49], v[132:133]
	v_pk_mul_f32 v[134:135], v[54:55], v[134:135]
	v_pk_mul_f32 v[132:133], v[52:53], v[132:133]
	v_pk_fma_f32 v[138:139], v[54:55], v[130:131], v[136:137] neg_lo:[0,0,1] neg_hi:[0,0,1]
	v_pk_fma_f32 v[136:137], v[52:53], v[128:129], v[140:141] neg_lo:[0,0,1] neg_hi:[0,0,1]
	v_pk_fma_f32 v[130:131], v[50:51], v[130:131], v[134:135]
	v_pk_fma_f32 v[128:129], v[48:49], v[128:129], v[132:133]
	s_and_b64 vcc, exec, s[6:7]
	s_mov_b64 s[26:27], -1
	s_cbranch_vccnz .LBB0_335
	v_or_b32_e32 v166, 0x80, v166
	v_cvt_pk_bf16_f32 v132, v136, v137
	v_cvt_pk_bf16_f32 v133, v138, v139
	v_lshl_add_u64 v[134:135], v[166:167], 1, s[22:23]
	global_store_dwordx2 v[134:135], v[132:133], off
	v_cvt_pk_bf16_f32 v132, v128, v129
	v_cvt_pk_bf16_f32 v133, v130, v131
	s_and_b64 vcc, exec, s[4:5]
	global_store_dwordx2 v[134:135], v[132:133], off offset:64
	s_cbranch_vccnz .LBB0_332
	v_lshl_add_u64 v[132:133], v[166:167], 2, s[56:57]
	global_store_dwordx4 v[132:133], v[136:139], off
	global_store_dwordx4 v[132:133], v[128:131], off offset:128

.LBB0_338:
	v_add_u32_e32 v168, 0x90, v162
	v_ashrrev_i32_e32 v169, 31, v168
	v_lshlrev_b64 v[166:167], 8, v[168:169]
	s_waitcnt vmcnt(0)
	v_pk_mul_f32 v[138:139], v[42:43], v[134:135]
	v_pk_mul_f32 v[136:137], v[40:41], v[132:133]
	v_pk_mul_f32 v[142:143], v[46:47], v[134:135]
	v_pk_mul_f32 v[140:141], v[44:45], v[132:133]
	v_or_b32_e32 v166, v166, v150
	v_pk_fma_f32 v[136:137], v[44:45], v[128:129], v[136:137] neg_lo:[0,0,1] neg_hi:[0,0,1]
	v_pk_fma_f32 v[138:139], v[46:47], v[130:131], v[138:139] neg_lo:[0,0,1] neg_hi:[0,0,1]
	v_pk_fma_f32 v[140:141], v[40:41], v[128:129], v[140:141]
	v_pk_fma_f32 v[142:143], v[42:43], v[130:131], v[142:143]
	s_and_b64 vcc, exec, s[6:7]
	s_mov_b64 s[26:27], -1
	s_cbranch_vccnz .LBB0_342
	v_cvt_pk_bf16_f32 v176, v136, v137
	v_cvt_pk_bf16_f32 v177, v138, v139
	v_lshl_add_u64 v[178:179], v[166:167], 1, s[22:23]
	global_store_dwordx2 v[178:179], v[176:177], off
	v_cvt_pk_bf16_f32 v176, v140, v141
	v_cvt_pk_bf16_f32 v177, v142, v143
	s_and_b64 vcc, exec, s[4:5]
	global_store_dwordx2 v[178:179], v[176:177], off offset:64
	s_cbranch_vccnz .LBB0_341
	v_lshl_add_u64 v[176:177], v[166:167], 2, s[56:57]
	global_store_dwordx4 v[176:177], v[136:139], off
	global_store_dwordx4 v[176:177], v[140:143], off offset:128

.LBB0_344:
	v_pk_mul_f32 v[136:137], v[34:35], v[134:135]
	v_pk_mul_f32 v[140:141], v[32:33], v[132:133]
	v_pk_mul_f32 v[134:135], v[38:39], v[134:135]
	v_pk_mul_f32 v[132:133], v[36:37], v[132:133]
	v_pk_fma_f32 v[138:139], v[38:39], v[130:131], v[136:137] neg_lo:[0,0,1] neg_hi:[0,0,1]
	v_pk_fma_f32 v[136:137], v[36:37], v[128:129], v[140:141] neg_lo:[0,0,1] neg_hi:[0,0,1]
	v_pk_fma_f32 v[130:131], v[34:35], v[130:131], v[134:135]
	v_pk_fma_f32 v[128:129], v[32:33], v[128:129], v[132:133]
	s_and_b64 vcc, exec, s[6:7]
	s_mov_b64 s[26:27], -1
	s_cbranch_vccnz .LBB0_350
	v_or_b32_e32 v166, 0x80, v166
	v_cvt_pk_bf16_f32 v132, v136, v137
	v_cvt_pk_bf16_f32 v133, v138, v139
	v_lshl_add_u64 v[134:135], v[166:167], 1, s[22:23]
	global_store_dwordx2 v[134:135], v[132:133], off
	v_cvt_pk_bf16_f32 v132, v128, v129
	v_cvt_pk_bf16_f32 v133, v130, v131
	s_and_b64 vcc, exec, s[4:5]
	global_store_dwordx2 v[134:135], v[132:133], off offset:64
	s_cbranch_vccnz .LBB0_347
	v_lshl_add_u64 v[132:133], v[166:167], 2, s[56:57]
	global_store_dwordx4 v[132:133], v[136:139], off
	global_store_dwordx4 v[132:133], v[128:131], off offset:128

.LBB0_353:
	v_add_u32_e32 v168, 0xa0, v162
	v_ashrrev_i32_e32 v169, 31, v168
	v_lshlrev_b64 v[166:167], 8, v[168:169]
	s_waitcnt vmcnt(0)
	v_pk_mul_f32 v[138:139], v[26:27], v[134:135]
	v_pk_mul_f32 v[136:137], v[24:25], v[132:133]
	v_pk_mul_f32 v[142:143], v[30:31], v[134:135]
	v_pk_mul_f32 v[140:141], v[28:29], v[132:133]
	v_or_b32_e32 v166, v166, v150
	v_pk_fma_f32 v[136:137], v[28:29], v[128:129], v[136:137] neg_lo:[0,0,1] neg_hi:[0,0,1]
	v_pk_fma_f32 v[138:139], v[30:31], v[130:131], v[138:139] neg_lo:[0,0,1] neg_hi:[0,0,1]
	v_pk_fma_f32 v[140:141], v[24:25], v[128:129], v[140:141]
	v_pk_fma_f32 v[142:143], v[26:27], v[130:131], v[142:143]
	s_and_b64 vcc, exec, s[6:7]
	s_mov_b64 s[26:27], -1
	s_cbranch_vccnz .LBB0_357
	v_cvt_pk_bf16_f32 v176, v136, v137
	v_cvt_pk_bf16_f32 v177, v138, v139
	v_lshl_add_u64 v[178:179], v[166:167], 1, s[22:23]
	global_store_dwordx2 v[178:179], v[176:177], off
	v_cvt_pk_bf16_f32 v176, v140, v141
	v_cvt_pk_bf16_f32 v177, v142, v143
	s_and_b64 vcc, exec, s[4:5]
	global_store_dwordx2 v[178:179], v[176:177], off offset:64
	s_cbranch_vccnz .LBB0_356
	v_lshl_add_u64 v[176:177], v[166:167], 2, s[56:57]
	global_store_dwordx4 v[176:177], v[136:139], off
	global_store_dwordx4 v[176:177], v[140:143], off offset:128

.LBB0_359:
	v_pk_mul_f32 v[136:137], v[18:19], v[134:135]
	v_pk_mul_f32 v[140:141], v[16:17], v[132:133]
	v_pk_mul_f32 v[134:135], v[22:23], v[134:135]
	v_pk_mul_f32 v[132:133], v[20:21], v[132:133]
	v_pk_fma_f32 v[138:139], v[22:23], v[130:131], v[136:137] neg_lo:[0,0,1] neg_hi:[0,0,1]
	v_pk_fma_f32 v[136:137], v[20:21], v[128:129], v[140:141] neg_lo:[0,0,1] neg_hi:[0,0,1]
	v_pk_fma_f32 v[130:131], v[18:19], v[130:131], v[134:135]
	v_pk_fma_f32 v[128:129], v[16:17], v[128:129], v[132:133]
	s_and_b64 vcc, exec, s[6:7]
	s_mov_b64 s[26:27], -1
	s_cbranch_vccnz .LBB0_365
	v_or_b32_e32 v166, 0x80, v166
	v_cvt_pk_bf16_f32 v132, v136, v137
	v_cvt_pk_bf16_f32 v133, v138, v139
	v_lshl_add_u64 v[134:135], v[166:167], 1, s[22:23]
	global_store_dwordx2 v[134:135], v[132:133], off
	v_cvt_pk_bf16_f32 v132, v128, v129
	v_cvt_pk_bf16_f32 v133, v130, v131
	s_and_b64 vcc, exec, s[4:5]
	global_store_dwordx2 v[134:135], v[132:133], off offset:64
	s_cbranch_vccnz .LBB0_362
	v_lshl_add_u64 v[132:133], v[166:167], 2, s[56:57]
	global_store_dwordx4 v[132:133], v[136:139], off
	global_store_dwordx4 v[132:133], v[128:131], off offset:128

.LBB0_368:
	v_add_u32_e32 v168, 0xb0, v162
	v_ashrrev_i32_e32 v169, 31, v168
	v_lshlrev_b64 v[166:167], 8, v[168:169]
	s_waitcnt vmcnt(0)
	v_pk_mul_f32 v[138:139], v[10:11], v[134:135]
	v_pk_mul_f32 v[136:137], v[8:9], v[132:133]
	v_pk_mul_f32 v[142:143], v[14:15], v[134:135]
	v_pk_mul_f32 v[140:141], v[12:13], v[132:133]
	v_or_b32_e32 v166, v166, v150
	v_pk_fma_f32 v[136:137], v[12:13], v[128:129], v[136:137] neg_lo:[0,0,1] neg_hi:[0,0,1]
	v_pk_fma_f32 v[138:139], v[14:15], v[130:131], v[138:139] neg_lo:[0,0,1] neg_hi:[0,0,1]
	v_pk_fma_f32 v[140:141], v[8:9], v[128:129], v[140:141]
	v_pk_fma_f32 v[142:143], v[10:11], v[130:131], v[142:143]
	s_and_b64 vcc, exec, s[6:7]
	s_mov_b64 s[8:9], -1
	s_cbranch_vccnz .LBB0_372
	v_cvt_pk_bf16_f32 v176, v136, v137
	v_cvt_pk_bf16_f32 v177, v138, v139
	v_lshl_add_u64 v[178:179], v[166:167], 1, s[22:23]
	global_store_dwordx2 v[178:179], v[176:177], off
	v_cvt_pk_bf16_f32 v176, v140, v141
	v_cvt_pk_bf16_f32 v177, v142, v143
	s_and_b64 vcc, exec, s[4:5]
	global_store_dwordx2 v[178:179], v[176:177], off offset:64
	s_cbranch_vccnz .LBB0_371
	v_lshl_add_u64 v[176:177], v[166:167], 2, s[56:57]
	global_store_dwordx4 v[176:177], v[136:139], off
	global_store_dwordx4 v[176:177], v[140:143], off offset:128

.LBB0_374:
	v_pk_mul_f32 v[136:137], v[2:3], v[134:135]
	v_pk_mul_f32 v[140:141], v[0:1], v[132:133]
	v_pk_mul_f32 v[134:135], v[6:7], v[134:135]
	v_pk_mul_f32 v[132:133], v[4:5], v[132:133]
	v_pk_fma_f32 v[138:139], v[6:7], v[130:131], v[136:137] neg_lo:[0,0,1] neg_hi:[0,0,1]
	v_pk_fma_f32 v[136:137], v[4:5], v[128:129], v[140:141] neg_lo:[0,0,1] neg_hi:[0,0,1]
	v_pk_fma_f32 v[130:131], v[2:3], v[130:131], v[134:135]
	v_pk_fma_f32 v[128:129], v[0:1], v[128:129], v[132:133]
	s_and_b64 vcc, exec, s[6:7]
	s_mov_b64 s[6:7], -1
	s_cbranch_vccnz .LBB0_378
	v_or_b32_e32 v166, 0x80, v166
	v_cvt_pk_bf16_f32 v132, v136, v137
	v_cvt_pk_bf16_f32 v133, v138, v139
	v_lshl_add_u64 v[134:135], v[166:167], 1, s[22:23]
	global_store_dwordx2 v[134:135], v[132:133], off
	v_cvt_pk_bf16_f32 v132, v128, v129
	v_cvt_pk_bf16_f32 v133, v130, v131
	s_and_b64 vcc, exec, s[4:5]
	global_store_dwordx2 v[134:135], v[132:133], off offset:64
	s_cbranch_vccnz .LBB0_377
	v_lshl_add_u64 v[132:133], v[166:167], 2, s[56:57]
	global_store_dwordx4 v[132:133], v[136:139], off
	global_store_dwordx4 v[132:133], v[128:131], off offset:128

.LBB0_384:
	s_andn2_b64 vcc, exec, s[6:7]
	v_lshl_add_u64 v[130:131], v[130:131], 2, s[58:59]
	s_cbranch_vccnz .LBB0_386
	global_store_dwordx4 v[130:131], v[124:127], off
	global_store_dwordx2 v[128:129], v[132:133], off offset:32
	global_store_dwordx4 v[130:131], v[120:123], off offset:64

.LBB0_388:
	s_andn2_b64 vcc, exec, s[6:7]
	s_cbranch_vccnz .LBB0_390
	global_store_dwordx4 v[130:131], v[116:119], off offset:512
	global_store_dwordx2 v[128:129], v[132:133], off offset:288
	global_store_dwordx4 v[130:131], v[112:115], off offset:576

.LBB0_392:
	s_andn2_b64 vcc, exec, s[6:7]
	v_lshl_add_u64 v[130:131], v[130:131], 2, s[58:59]
	s_cbranch_vccnz .LBB0_394
	global_store_dwordx4 v[130:131], v[108:111], off
	global_store_dwordx2 v[128:129], v[132:133], off offset:32
	global_store_dwordx4 v[130:131], v[104:107], off offset:64

.LBB0_396:
	s_andn2_b64 vcc, exec, s[6:7]
	s_cbranch_vccnz .LBB0_398
	global_store_dwordx4 v[130:131], v[100:103], off offset:512
	global_store_dwordx2 v[128:129], v[132:133], off offset:288
	global_store_dwordx4 v[130:131], v[96:99], off offset:576

.LBB0_400:
	s_andn2_b64 vcc, exec, s[6:7]
	v_lshl_add_u64 v[130:131], v[130:131], 2, s[58:59]
	s_cbranch_vccnz .LBB0_402
	global_store_dwordx4 v[130:131], v[92:95], off
	global_store_dwordx2 v[128:129], v[132:133], off offset:32
	global_store_dwordx4 v[130:131], v[88:91], off offset:64

.LBB0_404:
	s_andn2_b64 vcc, exec, s[6:7]
	s_cbranch_vccnz .LBB0_406
	global_store_dwordx4 v[130:131], v[84:87], off offset:512
	global_store_dwordx2 v[128:129], v[132:133], off offset:288
	global_store_dwordx4 v[130:131], v[80:83], off offset:576

.LBB0_408:
	s_andn2_b64 vcc, exec, s[6:7]
	v_lshl_add_u64 v[130:131], v[130:131], 2, s[58:59]
	s_cbranch_vccnz .LBB0_410
	global_store_dwordx4 v[130:131], v[76:79], off
	global_store_dwordx2 v[128:129], v[132:133], off offset:32
	global_store_dwordx4 v[130:131], v[72:75], off offset:64

.LBB0_412:
	s_andn2_b64 vcc, exec, s[6:7]
	s_cbranch_vccnz .LBB0_414
	global_store_dwordx4 v[130:131], v[68:71], off offset:512
	global_store_dwordx2 v[128:129], v[132:133], off offset:288
	global_store_dwordx4 v[130:131], v[64:67], off offset:576

.LBB0_416:
	s_andn2_b64 vcc, exec, s[6:7]
	v_lshl_add_u64 v[130:131], v[130:131], 2, s[58:59]
	s_cbranch_vccnz .LBB0_418
	global_store_dwordx4 v[130:131], v[60:63], off
	global_store_dwordx2 v[128:129], v[132:133], off offset:32
	global_store_dwordx4 v[130:131], v[56:59], off offset:64

.LBB0_420:
	s_andn2_b64 vcc, exec, s[6:7]
	s_cbranch_vccnz .LBB0_422
	global_store_dwordx4 v[130:131], v[52:55], off offset:512
	global_store_dwordx2 v[128:129], v[132:133], off offset:288
	global_store_dwordx4 v[130:131], v[48:51], off offset:576

.LBB0_424:
	s_andn2_b64 vcc, exec, s[6:7]
	v_lshl_add_u64 v[130:131], v[130:131], 2, s[58:59]
	s_cbranch_vccnz .LBB0_426
	global_store_dwordx4 v[130:131], v[44:47], off
	global_store_dwordx2 v[128:129], v[132:133], off offset:32
	global_store_dwordx4 v[130:131], v[40:43], off offset:64

.LBB0_428:
	s_andn2_b64 vcc, exec, s[6:7]
	s_cbranch_vccnz .LBB0_430
	global_store_dwordx4 v[130:131], v[36:39], off offset:512
	global_store_dwordx2 v[128:129], v[132:133], off offset:288
	global_store_dwordx4 v[130:131], v[32:35], off offset:576

.LBB0_432:
	s_andn2_b64 vcc, exec, s[6:7]
	v_lshl_add_u64 v[130:131], v[130:131], 2, s[58:59]
	s_cbranch_vccnz .LBB0_434
	global_store_dwordx4 v[130:131], v[28:31], off
	global_store_dwordx2 v[128:129], v[132:133], off offset:32
	global_store_dwordx4 v[130:131], v[24:27], off offset:64

.LBB0_436:
	s_andn2_b64 vcc, exec, s[6:7]
	s_cbranch_vccnz .LBB0_438
	global_store_dwordx4 v[130:131], v[20:23], off offset:512
	global_store_dwordx2 v[128:129], v[132:133], off offset:288
	global_store_dwordx4 v[130:131], v[16:19], off offset:576

.LBB0_440:
	s_andn2_b64 vcc, exec, s[6:7]
	v_lshl_add_u64 v[130:131], v[130:131], 2, s[58:59]
	s_cbranch_vccnz .LBB0_442
	global_store_dwordx4 v[130:131], v[12:15], off
	global_store_dwordx2 v[128:129], v[132:133], off offset:32
	global_store_dwordx4 v[130:131], v[8:11], off offset:64

.LBB0_444:
	s_andn2_b64 vcc, exec, s[6:7]
	s_cbranch_vccnz .LBB0_446
	global_store_dwordx4 v[130:131], v[4:7], off offset:512
	global_store_dwordx2 v[128:129], v[132:133], off offset:288
	global_store_dwordx4 v[130:131], v[0:3], off offset:576

.LBB0_550:
	s_cmp_gt_u32 s88, 7
	v_ashrrev_i32_e32 v163, 31, v162
	s_cselect_b64 s[8:9], -1, 0
	v_lshlrev_b64 v[166:167], 8, v[162:163]
	s_waitcnt vmcnt(0)
	v_pk_mul_f32 v[138:139], v[122:123], v[134:135]
	v_pk_mul_f32 v[136:137], v[120:121], v[132:133]
	v_pk_mul_f32 v[142:143], v[126:127], v[134:135]
	v_pk_mul_f32 v[140:141], v[124:125], v[132:133]
	v_cndmask_b32_e64 v164, 0, 1, s[4:5]
	v_or_b32_e32 v166, v166, v150
	v_pk_fma_f32 v[136:137], v[124:125], v[128:129], v[136:137] neg_lo:[0,0,1] neg_hi:[0,0,1]
	v_pk_fma_f32 v[138:139], v[126:127], v[130:131], v[138:139] neg_lo:[0,0,1] neg_hi:[0,0,1]
	v_pk_fma_f32 v[140:141], v[120:121], v[128:129], v[140:141]
	v_pk_fma_f32 v[142:143], v[122:123], v[130:131], v[142:143]
	s_mov_b64 s[6:7], -1
	s_and_b64 vcc, exec, s[8:9]
	v_cmp_ne_u32_e64 s[4:5], 1, v164
	s_cbranch_vccz .LBB0_554
	v_cvt_pk_bf16_f32 v164, v136, v137
	v_cvt_pk_bf16_f32 v165, v138, v139
	v_lshl_add_u64 v[168:169], v[166:167], 1, s[22:23]
	global_store_dwordx2 v[168:169], v[164:165], off
	v_cvt_pk_bf16_f32 v164, v140, v141
	v_cvt_pk_bf16_f32 v165, v142, v143
	s_and_b64 vcc, exec, s[4:5]
	global_store_dwordx2 v[168:169], v[164:165], off offset:64
	s_cbranch_vccnz .LBB0_553
	v_lshl_add_u64 v[164:165], v[166:167], 2, s[56:57]
	global_store_dwordx4 v[164:165], v[136:139], off
	global_store_dwordx4 v[164:165], v[140:143], off offset:128
